# v40 + P6 start: SS3/SSE loads issued before the GEMM prologue, RS0/RS1 1/rms tables computed by waves 0-3 after the first 8 tile loads are in flight
# speedup vs baseline: 1.0183x; 1.0183x over previous
.LBB0_745:
	s_or_b64 exec, exec, s[4:5]
	s_movk_i32 s1, 0x100
	v_cmp_gt_u32_e32 vcc, s1, v0
	s_barrier
	s_and_saveexec_b64 s[8:9], vcc
	s_cbranch_execz .LBB0_747
	s_ashr_i32 s1, s0, 31
	s_lshl_b64 s[0:1], s[0:1], 8
	v_or_b32_e32 v228, s0, v0
	v_mov_b32_e32 v229, s1
	v_lshl_add_u64 v[224:225], v[228:229], 4, s[24:25]
	global_load_dwordx4 v[224:227], v[224:225], off
	v_lshlrev_b64 v[228:229], 6, v[228:229]
	v_lshl_add_u64 v[244:245], s[80:81], 0, v[228:229]
	global_load_dwordx4 v[228:231], v[244:245], off
	global_load_dwordx4 v[232:235], v[244:245], off offset:16
	global_load_dwordx4 v[236:239], v[244:245], off offset:32
	global_load_dwordx4 v[240:243], v[244:245], off offset:48

.LBB0_752:
	v_lshrrev_b32_e32 v3, 5, v0
	v_lshlrev_b32_e32 v1, 4, v0
	v_and_b32_e32 v2, 32, v0
	v_and_b32_e32 v13, 24, v187
	v_and_b32_e32 v3, 4, v3
	v_bfe_u32 v4, v0, 2, 2
	v_bfe_u32 v12, v0, 2, 4
	v_bitop3_b32 v10, v1, v2, 48 bitop3:0x6c
	v_and_b32_e32 v11, 64, v0
	v_or3_b32 v3, v3, v4, v13
	v_lshrrev_b32_e32 v4, 3, v0
	v_or_b32_e32 v14, 0x2000, v1
	v_or_b32_e32 v2, v10, v11
	v_and_or_b32 v5, v4, 48, v12
	v_and_or_b32 v4, v4, 32, v3
	v_lshrrev_b32_e32 v1, 7, v14
	s_movk_i32 s1, 0x70
	v_lshl_or_b32 v164, v4, 11, v2
	v_and_or_b32 v4, v1, s1, v12
	s_movk_i32 s1, 0x60
	v_and_or_b32 v1, v1, s1, v3
	v_readlane_b32 s1, v251, 61
	s_add_i32 s4, s4, s1
	s_ashr_i32 s1, s4, 31
	s_lshr_b32 s1, s1, 27
	s_add_i32 s5, s4, s1
	s_ashr_i32 s1, s5, 5
	s_lshl_b32 s6, s1, 3
	s_sub_i32 s1, 64, s6
	s_min_i32 s7, s1, 8
	s_abs_i32 s8, s7
	v_cvt_f32_u32_e32 v3, s8
	v_lshl_or_b32 v168, v1, 11, v2
	s_sub_i32 s20, 0, s8
	s_andn2_b32 s5, s5, 31
	v_rcp_iflag_f32_e32 v1, v3
	s_sub_i32 s4, s4, s5
	s_abs_i32 s9, s4
	s_lshr_b32 s1, s36, 6
	v_mul_f32_e32 v1, 0x4f7ffffe, v1
	v_cvt_u32_f32_e32 v1, v1
	s_xor_b32 s5, s4, s7
	s_lshr_b32 s0, s36, 8
	s_lshl_b32 s37, s1, 10
	v_readfirstlane_b32 s21, v1
	s_mul_i32 s20, s20, s21
	s_mul_hi_u32 s20, s21, s20
	s_add_i32 s21, s21, s20
	s_mul_hi_u32 s20, s9, s21
	s_mul_i32 s21, s20, s8
	s_sub_i32 s9, s9, s21
	s_ashr_i32 s5, s5, 31
	s_add_i32 s21, s20, 1
	s_sub_i32 s22, s9, s8
	s_cmp_ge_u32 s9, s8
	s_cselect_b32 s20, s21, s20
	s_cselect_b32 s9, s22, s9
	s_add_i32 s21, s20, 1
	s_cmp_ge_u32 s9, s8
	s_cselect_b32 s8, s21, s20
	s_xor_b32 s8, s8, s5
	s_sub_i32 s24, s8, s5
	s_mul_i32 s5, s24, s7
	s_sub_i32 s4, s4, s5
	s_add_i32 s26, s6, s4
	s_ashr_i32 s27, s26, 31
	s_ashr_i32 s25, s24, 31
	s_lshl_b64 s[4:5], s[26:27], 19
	s_lshl_b64 s[6:7], s[24:25], 19
	v_readlane_b32 s8, v251, 49
	v_readlane_b32 s9, v251, 50
	s_add_u32 s30, s8, s6
	s_addc_u32 s31, s9, s7
	s_add_i32 s25, s37, 0
	s_add_i32 m0, s25, 0x10000
	v_lshl_or_b32 v162, v5, 11, v2
	global_load_lds_dwordx4 v164, s[30:31]
	s_add_i32 m0, s25, 0x12000
	s_add_u32 s6, s30, 0x40000
	global_load_lds_dwordx4 v168, s[30:31]
	s_addc_u32 s7, s31, 0
	s_add_i32 m0, s25, 0x14000
	v_lshl_or_b32 v166, v4, 11, v2
	global_load_lds_dwordx4 v164, s[6:7]
	s_add_i32 m0, s25, 0x16000
	s_add_u32 s28, s18, s4
	s_addc_u32 s29, s19, s5
	s_add_i32 s27, s25, 0x2000
	global_load_lds_dwordx4 v168, s[6:7]
	s_mov_b32 m0, s25
	s_add_u32 s4, s28, 0x40000
	global_load_lds_dwordx4 v162, s[28:29]
	s_mov_b32 m0, s27
	s_addc_u32 s5, s29, 0
	s_add_i32 s38, s25, 0x4000
	global_load_lds_dwordx4 v166, s[28:29]
	s_mov_b32 m0, s38
	s_add_i32 s39, s25, 0x6000
	global_load_lds_dwordx4 v162, s[4:5]
	s_mov_b32 m0, s39
	v_mov_b32_e32 v165, 0
	global_load_lds_dwordx4 v166, s[4:5]
	v_mov_b32_e32 v169, v165
	v_mov_b32_e32 v163, v165
	v_mov_b32_e32 v167, v165
	s_mov_b32 s40, 0
	v_lshl_add_u64 v[8:9], s[30:31], 0, v[164:165]
	v_lshl_add_u64 v[6:7], s[30:31], 0, v[168:169]
	v_lshl_add_u64 v[4:5], s[28:29], 0, v[162:163]
	v_readfirstlane_b32 s98, v0
	s_cmp_gt_u32 s98, 255
	s_cbranch_scc1 .Lmy_rs6_skip
	v_mov_b32_e32 v244, 0x358637bd
	v_mov_b32_e32 v247, 0xf800000
	v_mov_b32_e32 v245, 0x260
	v_lshlrev_b32_e32 v246, 2, v0
	v_add_u32_e32 v246, 0x22400, v246
	s_waitcnt vmcnt(12)
	v_add_f32_e32 v224, v224, v225
	v_add_f32_e32 v225, v226, v227
	v_add_f32_e32 v224, v224, v225
	s_waitcnt vmcnt(11)
	v_add_f32_e32 v225, v228, v229
	v_add_f32_e32 v226, v230, v231
	s_waitcnt vmcnt(10)
	v_add_f32_e32 v227, v232, v233
	v_add_f32_e32 v228, v234, v235
	s_waitcnt vmcnt(9)
	v_add_f32_e32 v229, v236, v237
	v_add_f32_e32 v230, v238, v239
	v_fmamk_f32 v224, v224, 0x3a800000, v244
	v_add_f32_e32 v225, v225, v226
	v_add_f32_e32 v226, v227, v228
	v_add_f32_e32 v227, v229, v230
	v_mul_f32_e32 v229, 0x4f800000, v224
	v_cmp_gt_f32_e32 vcc, v247, v224
	v_add_f32_e32 v225, 0, v225
	s_waitcnt vmcnt(8)
	v_add_f32_e32 v231, v240, v241
	v_cndmask_b32_e32 v224, v224, v229, vcc
	v_add_f32_e32 v232, v242, v243
	v_add_f32_e32 v225, v225, v226
	v_sqrt_f32_e32 v226, v224
	v_add_f32_e32 v228, v231, v232
	v_add_f32_e32 v225, v225, v227
	v_add_f32_e32 v225, v225, v228
	v_fmac_f32_e32 v244, 0x3a800000, v225
	v_mul_f32_e32 v225, 0x4f800000, v244
	v_add_u32_e32 v227, -1, v226
	v_cmp_gt_f32_e64 s[98:99], v247, v244
	v_add_u32_e32 v228, 1, v226
	v_fma_f32 v229, -v227, v226, v224
	v_cndmask_b32_e64 v225, v244, v225, s[98:99]
	v_fma_f32 v230, -v228, v226, v224
	v_sqrt_f32_e32 v231, v225
	v_cmp_ge_f32_e64 s[100:101], 0, v229
	s_nop 1
	v_cndmask_b32_e64 v226, v226, v227, s[100:101]
	v_cmp_lt_f32_e64 s[100:101], 0, v230
	s_nop 1
	v_cndmask_b32_e64 v226, v226, v228, s[100:101]
	v_mul_f32_e32 v227, 0x37800000, v226
	v_cndmask_b32_e32 v226, v226, v227, vcc
	v_add_u32_e32 v227, -1, v231
	v_cmp_class_f32_e32 vcc, v224, v245
	v_add_u32_e32 v228, 1, v231
	v_fma_f32 v229, -v228, v231, v225
	v_cndmask_b32_e32 v224, v226, v224, vcc
	v_fma_f32 v226, -v227, v231, v225
	v_cmp_ge_f32_e64 s[100:101], 0, v226
	v_div_scale_f32 v230, s[6:7], v224, v224, 1.0
	s_nop 0
	v_cndmask_b32_e64 v226, v231, v227, s[100:101]
	v_cmp_lt_f32_e64 s[100:101], 0, v229
	v_rcp_f32_e32 v227, v230
	v_div_scale_f32 v232, vcc, 1.0, v224, 1.0
	v_cndmask_b32_e64 v226, v226, v228, s[100:101]
	v_mul_f32_e32 v228, 0x37800000, v226
	v_cndmask_b32_e64 v226, v226, v228, s[98:99]
	v_cmp_class_f32_e64 s[98:99], v225, v245
	s_nop 1
	v_cndmask_b32_e64 v225, v226, v225, s[98:99]
	v_fma_f32 v226, -v230, v227, 1.0
	v_div_scale_f32 v228, s[6:7], v225, v225, 1.0
	v_fmac_f32_e32 v227, v226, v227
	v_rcp_f32_e32 v226, v228
	v_mul_f32_e32 v231, v232, v227
	v_fma_f32 v233, -v230, v231, v232
	v_fmac_f32_e32 v231, v233, v227
	v_fma_f32 v230, -v230, v231, v232
	v_fma_f32 v232, -v228, v226, 1.0
	v_div_scale_f32 v229, s[98:99], 1.0, v225, 1.0
	v_div_fmas_f32 v227, v230, v227, v231
	v_fmac_f32_e32 v226, v232, v226
	v_div_fixup_f32 v224, v227, v224, 1.0
	v_mul_f32_e32 v227, v229, v226
	ds_write_b32 v191, v224
	v_fma_f32 v224, -v228, v227, v229
	v_fmac_f32_e32 v227, v224, v226
	v_fma_f32 v224, -v228, v227, v229
	s_mov_b64 vcc, s[98:99]
	v_div_fmas_f32 v224, v224, v226, v227
	v_div_fixup_f32 v224, v224, v225, 1.0
	ds_write_b32 v246, v224
.Lmy_rs6_skip:
	s_cmp_lg_u32 s0, 1
	v_lshl_add_u64 v[2:3], s[28:29], 0, v[166:167]
	s_cbranch_scc1 .LBB0_754
	s_barrier
